# P6 work queue: next ticket fetched by an atomic issued right after the current item is decoded (round trip overlaps the item)
# speedup vs baseline: 1.0045x; 1.0013x over previous
.LBB0_1066:
	v_writelane_b32 v251, s36, 50
	v_writelane_b32 v253, s79, 0
	v_writelane_b32 v253, s78, 1
	v_writelane_b32 v251, s37, 51
	v_writelane_b32 v251, s54, 52
	v_writelane_b32 v253, s76, 2
	s_nop 0
	v_writelane_b32 v251, s55, 53
	v_writelane_b32 v253, s77, 3
	v_writelane_b32 v251, s96, 54
	v_writelane_b32 v253, s69, 4
	v_writelane_b32 v251, s97, 55
	v_writelane_b32 v253, s72, 5
	v_writelane_b32 v251, s66, 56
	s_nop 0
	v_writelane_b32 v253, s73, 6
	v_writelane_b32 v251, s67, 57
	v_writelane_b32 v253, s70, 7
	v_writelane_b32 v251, s75, 58
	v_writelane_b32 v251, s74, 59
	v_writelane_b32 v253, s71, 8
	v_writelane_b32 v253, s68, 9
	v_writelane_b32 v251, s59, 60
	v_writelane_b32 v253, s58, 10
	v_writelane_b32 v251, s60, 61
	s_nop 0
	v_writelane_b32 v253, s59, 11
	v_writelane_b32 v251, s61, 62
	v_writelane_b32 v253, s56, 12
	v_writelane_b32 v251, s63, 63
	s_nop 0
	v_writelane_b32 v253, s57, 13
	s_or_b64 exec, exec, s[30:31]
	v_readlane_b32 s0, v251, 10
	s_add_i32 s1, s0, 0xffffe200
	v_writelane_b32 v253, s1, 14
	s_lshl_b32 s1, s0, 8
	s_cmp_gt_u32 s62, 63
	v_writelane_b32 v253, s1, 15
	s_cselect_b64 s[2:3], -1, 0
	v_writelane_b32 v253, s2, 16
	s_cmp_eq_u32 s0, 7
	s_cselect_b64 s[0:1], -1, 0
	v_writelane_b32 v253, s3, 17
	s_add_u32 s56, s40, 0x4a5c000
	v_writelane_b32 v253, s0, 18
	s_addc_u32 s57, s41, 0
	s_mov_b64 s[34:35], s[64:65]
	v_writelane_b32 v253, s1, 19
	s_add_u32 s0, s40, 0x4220000
	v_writelane_b32 v253, s0, 20
	s_addc_u32 s0, s41, 0
	v_writelane_b32 v253, s0, 21
	s_add_i32 s0, 0, 0x22000
	v_writelane_b32 v253, s0, 22
	s_add_i32 s0, 0, 0x11000
	v_writelane_b32 v253, s0, 23
	s_add_i32 s0, 0, 0x19800
	v_writelane_b32 v253, s0, 24
	s_add_i32 s0, 0, 0x1dc00
	v_writelane_b32 v253, s0, 25
	s_add_i32 s0, 0, 0x2643c
	v_writelane_b32 v253, s0, 26
	s_add_i32 s0, 0, 0x2647c
	v_writelane_b32 v253, s0, 27
	s_add_i32 s0, 0, 0x264bc
	v_writelane_b32 v253, s0, 28
	s_add_i32 s0, 0, 0x264fc
	v_writelane_b32 v253, s0, 29
	s_add_i32 s0, 0, 0x2653c
	v_writelane_b32 v253, s0, 30
	s_add_i32 s0, 0, 0x2657c
	v_writelane_b32 v253, s0, 31
	s_add_i32 s0, 0, 0x265bc
	v_writelane_b32 v253, s0, 32
	s_add_i32 s0, 0, 0x265fc
	v_writelane_b32 v253, s0, 33
	v_writelane_b32 v253, s34, 34
	v_readlane_b32 s36, v252, 48
	v_readlane_b32 s42, v252, 54
	v_writelane_b32 v253, s35, 35
	v_readlane_b32 s43, v252, 55
	v_readlane_b32 s48, v252, 60
	v_readlane_b32 s49, v252, 61
	v_readlane_b32 s50, v252, 62
	v_readlane_b32 s51, v252, 63
	v_writelane_b32 v253, s56, 36
	v_mov_b32_e32 v187, 0
	s_add_i32 s76, 0, 0x26a00
	v_readlane_b32 s48, v251, 0
	v_readlane_b32 s42, v251, 37
	v_writelane_b32 v253, s57, 37
	s_mov_b32 s81, 0
	s_movk_i32 s77, 0x2600
	s_movk_i32 s78, 0x1000
	s_mov_b32 s33, 0xbfb8aa3b
	v_mov_b32_e32 v199, 0x3eaaaaab
	s_mov_b32 s58, 0x800000
	s_mov_b32 s59, 0x3f317217
	s_mov_b32 s96, 0x7f800000
	s_mov_b32 s97, 0x3dcccccd
	s_movk_i32 s79, 0x2000
	v_mov_b32_e32 v200, s76
	v_mbcnt_hi_u32_b32 v198, -1, v250
	v_mov_b32_e32 v201, 0x41b17218
	v_mov_b32_e32 v0, v187
	v_mov_b32_e32 v1, v187
	v_mov_b32_e32 v2, v187
	v_mov_b32_e32 v3, v187
	v_bfrev_b32_e32 v202, 0.5
	v_readlane_b32 s37, v252, 49
	v_readlane_b32 s38, v252, 50
	v_readlane_b32 s39, v252, 51
	v_readlane_b32 s40, v252, 52
	v_readlane_b32 s41, v252, 53
	v_readlane_b32 s49, v251, 1
	v_readlane_b32 s50, v251, 2
	v_readlane_b32 s51, v251, 3
	v_readlane_b32 s52, v251, 4
	v_readlane_b32 s53, v251, 5
	v_readlane_b32 s54, v251, 6
	v_readlane_b32 s55, v251, 7
	v_readlane_b32 s43, v251, 38
	v_writelane_b32 v253, s76, 38
	s_waitcnt lgkmcnt(0)
	s_barrier
	v_readlane_b32 s44, v252, 56
	v_readlane_b32 s45, v252, 57
	v_readlane_b32 s46, v252, 58
	v_readlane_b32 s47, v252, 59
	s_and_saveexec_b64 s[98:99], s[34:35]
	s_cbranch_execz .Lq_pf0
	v_mov_b32_e32 v239, 1
	global_atomic_add v239, v187, v239, s[54:55] sc0
.Lq_pf0:
	s_or_b64 exec, exec, s[98:99]
	s_branch .LBB0_1070

.LBB0_1070:
	s_barrier
	s_and_saveexec_b64 s[0:1], s[34:35]
	s_cbranch_execz .LBB0_1074
	s_mov_b64 s[4:5], exec
	v_mbcnt_lo_u32_b32 v4, s4, 0
	v_mbcnt_hi_u32_b32 v4, s5, v4
	v_cmp_eq_u32_e32 vcc, 0, v4
	s_and_saveexec_b64 s[2:3], vcc
	s_cbranch_execz .LBB0_1073
	s_bcnt1_i32_b64 s4, s[4:5]
	v_mov_b32_e32 v5, s4
	s_waitcnt vmcnt(0)
	v_mov_b32_e32 v5, v239

.LBB0_1074:
	s_or_b64 exec, exec, s[0:1]
	s_waitcnt lgkmcnt(0)
	s_barrier
	ds_read_b32 v4, v200
	s_movk_i32 s0, 0x43f
	s_waitcnt lgkmcnt(0)
	v_cmp_lt_i32_e32 vcc, s0, v4
	v_readfirstlane_b32 s44, v4
	s_mov_b64 s[0:1], -1
	s_cbranch_vccnz .LBB0_1069
	s_and_saveexec_b64 s[98:99], s[34:35]
	s_cbranch_execz .Lq_pf1
	v_mov_b32_e32 v239, 1
	global_atomic_add v239, v187, v239, s[54:55] sc0
.Lq_pf1:
	s_or_b64 exec, exec, s[98:99]
	s_cmpk_gt_i32 s44, 0xbf
	s_cbranch_scc0 .LBB0_1183
	s_cmpk_gt_u32 s44, 0x2bf
	s_cbranch_scc0 .LBB0_1132
	s_cmpk_gt_u32 s44, 0x3bf
	s_cbranch_scc0 .LBB0_1099
	v_mov_b32_e32 v60, v184
	s_lshl_b32 s0, s44, 3
	s_waitcnt vmcnt(0)
	v_ashrrev_i32_e32 v20, 4, v60
	v_readlane_b32 s1, v253, 14
	v_lshlrev_b32_e32 v62, 3, v20
	v_readlane_b32 s2, v251, 27
	s_add_i32 s6, s1, s0
	v_ashrrev_i32_e32 v63, 31, v62
	v_readlane_b32 s3, v251, 28
	s_and_b32 s4, s6, 31
	v_and_b32_e32 v68, 15, v60
	v_cmp_lt_i32_e64 s[0:1], 1, v20
	v_cmp_gt_i32_e32 vcc, 2, v20
	v_lshl_add_u64 v[4:5], v[62:63], 1, s[2:3]
	v_mov_b32_e32 v24, 0
	v_mov_b32_e32 v28, 0
	v_mov_b32_e32 v29, 0
	v_mov_b32_e32 v30, 0
	v_mov_b32_e32 v31, 0
	s_and_saveexec_b64 s[2:3], vcc
	s_cbranch_execz .LBB0_1080
	s_lshl_b32 s5, s4, 12
	v_lshl_or_b32 v186, v68, 5, s5
	v_lshl_add_u64 v[6:7], v[4:5], 0, v[186:187]
	global_load_dwordx4 v[28:31], v[6:7], off
